# hand-written P10e final rmsnorm: mod5/g_final rows hoisted to registers, next token rows prefetched (double buffer), DPP wave sum
# speedup vs baseline: 1.0292x; 1.0035x over previous
; __device__ __forceinline__ void final_row_load(FinalRow& r, const Params& p, const unsigned char* ws, int tok, int lane) {
;     const bf16* mrow = (const bf16*)(ws + WS_MIX) + (size_t)tok * D; const bf16* prow = (const bf16*)(ws + WS_PO) + (size_t)tok * D;
; #pragma unroll
;     for (int j = 0; j < 8; ++j) { const int el = 4 * lane + 256 * j; r.m[j] = *(const u32x2*)(mrow + el); r.q[j] = *(const u32x2*)(prow + el); }
; }
; __device__ __forceinline__ void peer_final(Frame& F, const Params& p) {
;     const float* modf = (const float*)(F.ws + WS_MODF);
;     const int lane = F.lane, gw = F.bx * NWAVES + F.wave, NGW = F.G * NWAVES;
;     FinalRow rn;
;     if (gw < NTOK) final_row_load(rn, p, F.ws, gw, lane);
;     for (int tok = gw; tok < NTOK; tok += NGW) {
;         FinalRow r = rn;
;         if (tok + NGW < NTOK) final_row_load(rn, p, F.ws, tok + NGW, lane);
;         float* hrow = p.out + (size_t)tok * D;
;         const float* m5 = modf + (size_t)(tok >> 14) * 12288 + 5 * D; float ss = 0.f;
;         f32x4 v[8];
; #pragma unroll
.LBB0_2210:
	s_or_b64 exec, exec, s[2:3]
	s_and_b64 vcc, exec, s[38:39]
	s_waitcnt lgkmcnt(0)
	s_barrier
	v_mbcnt_lo_u32_b32 v0, -1, 0
	v_mbcnt_hi_u32_b32 v0, -1, v0
	s_cbranch_vccnz .LBB0_2215
	s_load_dwordx2 s[8:9], s[0:1], 0x100
	s_load_dwordx2 s[6:7], s[0:1], 0x108
	v_lshlrev_b32_e32 v1, 3, v0
	v_lshlrev_b32_e32 v2, 4, v0
	v_mov_b32_e32 v202, 0x358637bd
	s_mov_b32 s26, 0xffff0000
	s_lshl_b32 s12, s60, 12
	s_add_u32 s2, s56, s12
	s_addc_u32 s3, s57, 0
	s_add_u32 s2, s2, 0x2e000000
	s_addc_u32 s3, s3, 0
	s_add_u32 s4, s64, s12
	s_addc_u32 s5, s65, 0
	global_load_dwordx2 v[72:73], v1, s[2:3]
	global_load_dwordx2 v[74:75], v1, s[2:3] offset:512
	global_load_dwordx2 v[76:77], v1, s[2:3] offset:1024
	global_load_dwordx2 v[78:79], v1, s[2:3] offset:1536
	global_load_dwordx2 v[80:81], v1, s[2:3] offset:2048
	global_load_dwordx2 v[82:83], v1, s[2:3] offset:2560
	global_load_dwordx2 v[84:85], v1, s[2:3] offset:3072
	global_load_dwordx2 v[86:87], v1, s[2:3] offset:3584
	global_load_dwordx2 v[88:89], v1, s[4:5]
	global_load_dwordx2 v[90:91], v1, s[4:5] offset:512
	global_load_dwordx2 v[92:93], v1, s[4:5] offset:1024
	global_load_dwordx2 v[94:95], v1, s[4:5] offset:1536
	global_load_dwordx2 v[96:97], v1, s[4:5] offset:2048
	global_load_dwordx2 v[98:99], v1, s[4:5] offset:2560
	global_load_dwordx2 v[100:101], v1, s[4:5] offset:3072
	global_load_dwordx2 v[102:103], v1, s[4:5] offset:3584
	s_waitcnt lgkmcnt(0)
	s_lshl_b32 s13, s60, 13
	s_add_u32 s6, s6, s13
	s_addc_u32 s7, s7, 0
	s_add_u32 s24, s6, 0x1000
	s_addc_u32 s25, s7, 0
	s_add_u32 s14, s8, 0x1000
	s_addc_u32 s15, s9, 0
	global_load_dwordx4 v[8:11], v2, s[8:9]
	global_load_dwordx4 v[12:15], v2, s[8:9] offset:1024
	global_load_dwordx4 v[16:19], v2, s[8:9] offset:2048
	global_load_dwordx4 v[20:23], v2, s[8:9] offset:3072
	global_load_dwordx4 v[24:27], v2, s[14:15]
	global_load_dwordx4 v[28:31], v2, s[14:15] offset:1024
	global_load_dwordx4 v[32:35], v2, s[14:15] offset:2048
	global_load_dwordx4 v[36:39], v2, s[14:15] offset:3072
	s_lshr_b32 s16, s60, 14
	s_mul_i32 s12, s16, 0xc000
	s_add_u32 s10, s56, s12
	s_addc_u32 s11, s57, 0
	s_add_u32 s10, s10, 0x60a000
	s_addc_u32 s11, s11, 0
	s_add_u32 s18, s10, 0x1000
	s_addc_u32 s19, s11, 0
	global_load_dwordx4 v[40:43], v2, s[10:11]
	global_load_dwordx4 v[44:47], v2, s[10:11] offset:1024
	global_load_dwordx4 v[48:51], v2, s[10:11] offset:2048
	global_load_dwordx4 v[52:55], v2, s[10:11] offset:3072
	global_load_dwordx4 v[56:59], v2, s[18:19]
	global_load_dwordx4 v[60:63], v2, s[18:19] offset:1024
	global_load_dwordx4 v[64:67], v2, s[18:19] offset:2048
	global_load_dwordx4 v[68:71], v2, s[18:19] offset:3072
	s_mov_b32 s17, 1
	s_lshl_b32 s20, s54, 12
	s_lshl_b32 s21, s54, 13
.Lmy_fin_loop:
.Lmy_fin_A:
	s_add_i32 s22, s60, s54
	s_cmp_gt_i32 s22, 0x7fff
	s_cbranch_scc1 .Lmy_fin_last_A
	s_add_u32 s2, s2, s20
	s_addc_u32 s3, s3, 0
	s_add_u32 s4, s4, s20
	s_addc_u32 s5, s5, 0
	global_load_dwordx2 v[104:105], v1, s[2:3]
	global_load_dwordx2 v[106:107], v1, s[2:3] offset:512
	global_load_dwordx2 v[108:109], v1, s[2:3] offset:1024
	global_load_dwordx2 v[110:111], v1, s[2:3] offset:1536
	global_load_dwordx2 v[112:113], v1, s[2:3] offset:2048
	global_load_dwordx2 v[114:115], v1, s[2:3] offset:2560
	global_load_dwordx2 v[116:117], v1, s[2:3] offset:3072
	global_load_dwordx2 v[118:119], v1, s[2:3] offset:3584
	global_load_dwordx2 v[120:121], v1, s[4:5]
	global_load_dwordx2 v[122:123], v1, s[4:5] offset:512
	global_load_dwordx2 v[124:125], v1, s[4:5] offset:1024
	global_load_dwordx2 v[126:127], v1, s[4:5] offset:1536
	global_load_dwordx2 v[128:129], v1, s[4:5] offset:2048
	global_load_dwordx2 v[130:131], v1, s[4:5] offset:2560
	global_load_dwordx2 v[132:133], v1, s[4:5] offset:3072
	global_load_dwordx2 v[134:135], v1, s[4:5] offset:3584
	s_cmp_eq_u32 s17, 0
	s_cbranch_scc1 .Lmy_fin_w24_A
	s_waitcnt vmcnt(16)
	s_mov_b32 s17, 0
.Lmy_fin_w24_A:
	s_waitcnt vmcnt(24)
	s_branch .Lmy_fin_go_A

; __device__ __forceinline__ float bf_lo(unsigned w) { return __uint_as_float(w << 16); }
; __device__ __forceinline__ float bf_hi(unsigned w) { return __uint_as_float(w & 0xffff0000u); }
; __device__ __forceinline__ void peer_final(Frame& F, const Params& p) {
;     ...
;         const float* m5 = modf + (size_t)(tok >> 14) * 12288 + 5 * D; float ss = 0.f;
;         f32x4 v[8];
; #pragma unroll
;         for (int j = 0; j < 8; ++j) {
;             const int el = 4 * lane + 256 * j; const f32x4 g4 = *(const f32x4*)(m5 + el);
;             const float mf[4] = {bf_lo(r.m[j].x), bf_hi(r.m[j].x), bf_lo(r.m[j].y), bf_hi(r.m[j].y)}, pf[4] = {bf_lo(r.q[j].x), bf_hi(r.q[j].x), bf_lo(r.q[j].y), bf_hi(r.q[j].y)};
; #pragma unroll
;             for (int i = 0; i < 4; ++i) { const float t = mf[i] + g4[i] * pf[i]; v[j][i] = t; ss += t * t; }
.Lmy_fin_go_A:
	s_lshr_b32 s23, s60, 14
	s_cmp_eq_u32 s23, s16
	s_cbranch_scc1 .Lmy_fin_nob_A
	s_mov_b32 s16, s23
	s_add_u32 s10, s10, 0xc000
	s_addc_u32 s11, s11, 0
	s_add_u32 s18, s18, 0xc000
	s_addc_u32 s19, s19, 0
	global_load_dwordx4 v[40:43], v2, s[10:11]
	global_load_dwordx4 v[44:47], v2, s[10:11] offset:1024
	global_load_dwordx4 v[48:51], v2, s[10:11] offset:2048
	global_load_dwordx4 v[52:55], v2, s[10:11] offset:3072
	global_load_dwordx4 v[56:59], v2, s[18:19]
	global_load_dwordx4 v[60:63], v2, s[18:19] offset:1024
	global_load_dwordx4 v[64:67], v2, s[18:19] offset:2048
	global_load_dwordx4 v[68:71], v2, s[18:19] offset:3072
	s_waitcnt vmcnt(0)
.Lmy_fin_nob_A:
	v_lshlrev_b32_e32 v168, 16, v72
	v_and_b32_e32 v169, s26, v72
	v_lshlrev_b32_e32 v170, 16, v73
	v_and_b32_e32 v171, s26, v73
	v_lshlrev_b32_e32 v172, 16, v88
	v_and_b32_e32 v173, s26, v88
	v_lshlrev_b32_e32 v174, 16, v89
	v_and_b32_e32 v175, s26, v89
	v_fma_f32 v136, v40, v172, v168
	v_fma_f32 v137, v41, v173, v169
	v_fma_f32 v138, v42, v174, v170
	v_fma_f32 v139, v43, v175, v171
	v_mul_f32_e32 v200, v136, v136
	v_mul_f32_e32 v201, v137, v137
	v_fmac_f32_e32 v200, v138, v138
	v_fmac_f32_e32 v201, v139, v139
	v_lshlrev_b32_e32 v168, 16, v74
	v_and_b32_e32 v169, s26, v74
	v_lshlrev_b32_e32 v170, 16, v75
	v_and_b32_e32 v171, s26, v75
	v_lshlrev_b32_e32 v172, 16, v90
	v_and_b32_e32 v173, s26, v90
	v_lshlrev_b32_e32 v174, 16, v91
	v_and_b32_e32 v175, s26, v91
	v_fma_f32 v140, v44, v172, v168
	v_fma_f32 v141, v45, v173, v169
	v_fma_f32 v142, v46, v174, v170
	v_fma_f32 v143, v47, v175, v171
	v_fmac_f32_e32 v200, v140, v140
	v_fmac_f32_e32 v201, v141, v141
	v_fmac_f32_e32 v200, v142, v142
	v_fmac_f32_e32 v201, v143, v143
	v_lshlrev_b32_e32 v168, 16, v76
	v_and_b32_e32 v169, s26, v76
	v_lshlrev_b32_e32 v170, 16, v77
	v_and_b32_e32 v171, s26, v77
	v_lshlrev_b32_e32 v172, 16, v92
	v_and_b32_e32 v173, s26, v92
	v_lshlrev_b32_e32 v174, 16, v93
	v_and_b32_e32 v175, s26, v93
	v_fma_f32 v144, v48, v172, v168
	v_fma_f32 v145, v49, v173, v169
	v_fma_f32 v146, v50, v174, v170
	v_fma_f32 v147, v51, v175, v171
	v_fmac_f32_e32 v200, v144, v144
	v_fmac_f32_e32 v201, v145, v145
	v_fmac_f32_e32 v200, v146, v146
	v_fmac_f32_e32 v201, v147, v147
	v_lshlrev_b32_e32 v168, 16, v78
	v_and_b32_e32 v169, s26, v78
	v_lshlrev_b32_e32 v170, 16, v79
	v_and_b32_e32 v171, s26, v79
	v_lshlrev_b32_e32 v172, 16, v94
	v_and_b32_e32 v173, s26, v94
	v_lshlrev_b32_e32 v174, 16, v95
	v_and_b32_e32 v175, s26, v95
	v_fma_f32 v148, v52, v172, v168
	v_fma_f32 v149, v53, v173, v169
	v_fma_f32 v150, v54, v174, v170
	v_fma_f32 v151, v55, v175, v171
	v_fmac_f32_e32 v200, v148, v148
	v_fmac_f32_e32 v201, v149, v149
	v_fmac_f32_e32 v200, v150, v150
	v_fmac_f32_e32 v201, v151, v151
	v_lshlrev_b32_e32 v168, 16, v80
	v_and_b32_e32 v169, s26, v80
	v_lshlrev_b32_e32 v170, 16, v81
	v_and_b32_e32 v171, s26, v81
	v_lshlrev_b32_e32 v172, 16, v96
	v_and_b32_e32 v173, s26, v96
	v_lshlrev_b32_e32 v174, 16, v97
	v_and_b32_e32 v175, s26, v97
	v_fma_f32 v152, v56, v172, v168
	v_fma_f32 v153, v57, v173, v169
	v_fma_f32 v154, v58, v174, v170
	v_fma_f32 v155, v59, v175, v171
	v_fmac_f32_e32 v200, v152, v152
	v_fmac_f32_e32 v201, v153, v153
	v_fmac_f32_e32 v200, v154, v154
	v_fmac_f32_e32 v201, v155, v155
	v_lshlrev_b32_e32 v168, 16, v82
	v_and_b32_e32 v169, s26, v82
	v_lshlrev_b32_e32 v170, 16, v83
	v_and_b32_e32 v171, s26, v83
	v_lshlrev_b32_e32 v172, 16, v98
	v_and_b32_e32 v173, s26, v98
	v_lshlrev_b32_e32 v174, 16, v99
	v_and_b32_e32 v175, s26, v99
	v_fma_f32 v156, v60, v172, v168
	v_fma_f32 v157, v61, v173, v169
	v_fma_f32 v158, v62, v174, v170
	v_fma_f32 v159, v63, v175, v171
	v_fmac_f32_e32 v200, v156, v156
	v_fmac_f32_e32 v201, v157, v157
	v_fmac_f32_e32 v200, v158, v158
	v_fmac_f32_e32 v201, v159, v159
	v_lshlrev_b32_e32 v168, 16, v84
	v_and_b32_e32 v169, s26, v84
	v_lshlrev_b32_e32 v170, 16, v85
	v_and_b32_e32 v171, s26, v85
	v_lshlrev_b32_e32 v172, 16, v100
	v_and_b32_e32 v173, s26, v100
	v_lshlrev_b32_e32 v174, 16, v101
	v_and_b32_e32 v175, s26, v101
	v_fma_f32 v160, v64, v172, v168
	v_fma_f32 v161, v65, v173, v169
	v_fma_f32 v162, v66, v174, v170
	v_fma_f32 v163, v67, v175, v171
	v_fmac_f32_e32 v200, v160, v160
	v_fmac_f32_e32 v201, v161, v161
	v_fmac_f32_e32 v200, v162, v162
	v_fmac_f32_e32 v201, v163, v163
	v_lshlrev_b32_e32 v168, 16, v86
	v_and_b32_e32 v169, s26, v86
	v_lshlrev_b32_e32 v170, 16, v87
	v_and_b32_e32 v171, s26, v87
	v_lshlrev_b32_e32 v172, 16, v102
	v_and_b32_e32 v173, s26, v102
	v_lshlrev_b32_e32 v174, 16, v103
	v_and_b32_e32 v175, s26, v103
	v_fma_f32 v164, v68, v172, v168
	v_fma_f32 v165, v69, v173, v169
; __device__ __forceinline__ void peer_final(Frame& F, const Params& p) {
;     ...
;     for (int tok = gw; tok < NTOK; tok += NGW) {
;         FinalRow r = rn;
;         if (tok + NGW < NTOK) final_row_load(rn, p, F.ws, tok + NGW, lane);
;     ...
;             for (int i = 0; i < 4; ++i) { const float t = mf[i] + g4[i] * pf[i]; v[j][i] = t; ss += t * t; }
;         }
;         const float rstd = rsqrtf(wave_sum(ss, lane) * (1.f / D) + 1e-6f);
; #pragma unroll
;         for (int j = 0; j < 8; ++j) {
;             const int el = 4 * lane + 256 * j; const f32x4 gf = *(const f32x4*)(p.in[32] + el);
;             *(f32x4*)(hrow + el) = (f32x4){v[j][0] * rstd * gf[0], v[j][1] * rstd * gf[1], v[j][2] * rstd * gf[2], v[j][3] * rstd * gf[3]};
;         }
	v_fma_f32 v166, v70, v174, v170
	v_fma_f32 v167, v71, v175, v171
	v_fmac_f32_e32 v200, v164, v164
	v_fmac_f32_e32 v201, v165, v165
	v_fmac_f32_e32 v200, v166, v166
	v_fmac_f32_e32 v201, v167, v167
	v_add_f32_e32 v200, v200, v201
	s_nop 1
	v_add_f32_dpp v200, v200, v200 quad_perm:[1,0,3,2] row_mask:0xf bank_mask:0xf
	s_nop 1
	v_add_f32_dpp v200, v200, v200 quad_perm:[2,3,0,1] row_mask:0xf bank_mask:0xf
	s_nop 1
	v_add_f32_dpp v200, v200, v200 row_half_mirror row_mask:0xf bank_mask:0xf
	s_nop 1
	v_add_f32_dpp v200, v200, v200 row_mirror row_mask:0xf bank_mask:0xf
	s_nop 1
	v_readlane_b32 s27, v200, 0
	v_readlane_b32 s28, v200, 16
	v_readlane_b32 s29, v200, 32
	v_readlane_b32 s30, v200, 48
	s_nop 1
	v_mov_b32_e32 v201, s27
	v_add_f32_e32 v201, s28, v201
	v_add_f32_e32 v201, s29, v201
	v_add_f32_e32 v201, s30, v201
	v_fmamk_f32 v201, v201, 0x3a000000, v202
	v_rsq_f32_e32 v201, v201
	s_nop 0
	v_mul_f32_e32 v136, v136, v201
	v_mul_f32_e32 v137, v137, v201
	v_mul_f32_e32 v138, v138, v201
	v_mul_f32_e32 v139, v139, v201
	v_mul_f32_e32 v140, v140, v201
	v_mul_f32_e32 v141, v141, v201
	v_mul_f32_e32 v142, v142, v201
	v_mul_f32_e32 v143, v143, v201
	v_mul_f32_e32 v144, v144, v201
	v_mul_f32_e32 v145, v145, v201
	v_mul_f32_e32 v146, v146, v201
	v_mul_f32_e32 v147, v147, v201
	v_mul_f32_e32 v148, v148, v201
	v_mul_f32_e32 v149, v149, v201
	v_mul_f32_e32 v150, v150, v201
	v_mul_f32_e32 v151, v151, v201
	v_mul_f32_e32 v152, v152, v201
	v_mul_f32_e32 v153, v153, v201
	v_mul_f32_e32 v154, v154, v201
	v_mul_f32_e32 v155, v155, v201
	v_mul_f32_e32 v156, v156, v201
	v_mul_f32_e32 v157, v157, v201
	v_mul_f32_e32 v158, v158, v201
	v_mul_f32_e32 v159, v159, v201
	v_mul_f32_e32 v160, v160, v201
	v_mul_f32_e32 v161, v161, v201
	v_mul_f32_e32 v162, v162, v201
	v_mul_f32_e32 v163, v163, v201
	v_mul_f32_e32 v164, v164, v201
	v_mul_f32_e32 v165, v165, v201
	v_mul_f32_e32 v166, v166, v201
	v_mul_f32_e32 v167, v167, v201
	v_mul_f32_e32 v136, v8, v136
	v_mul_f32_e32 v137, v9, v137
	v_mul_f32_e32 v138, v10, v138
	v_mul_f32_e32 v139, v11, v139
	v_mul_f32_e32 v140, v12, v140
	v_mul_f32_e32 v141, v13, v141
	v_mul_f32_e32 v142, v14, v142
	v_mul_f32_e32 v143, v15, v143
	v_mul_f32_e32 v144, v16, v144
	v_mul_f32_e32 v145, v17, v145
	v_mul_f32_e32 v146, v18, v146
	v_mul_f32_e32 v147, v19, v147
	v_mul_f32_e32 v148, v20, v148
	v_mul_f32_e32 v149, v21, v149
	v_mul_f32_e32 v150, v22, v150
	v_mul_f32_e32 v151, v23, v151
	v_mul_f32_e32 v152, v24, v152
	v_mul_f32_e32 v153, v25, v153
	v_mul_f32_e32 v154, v26, v154
	v_mul_f32_e32 v155, v27, v155
	v_mul_f32_e32 v156, v28, v156
	v_mul_f32_e32 v157, v29, v157
	v_mul_f32_e32 v158, v30, v158
	v_mul_f32_e32 v159, v31, v159
	v_mul_f32_e32 v160, v32, v160
	v_mul_f32_e32 v161, v33, v161
	v_mul_f32_e32 v162, v34, v162
	v_mul_f32_e32 v163, v35, v163
	v_mul_f32_e32 v164, v36, v164
	v_mul_f32_e32 v165, v37, v165
	v_mul_f32_e32 v166, v38, v166
	v_mul_f32_e32 v167, v39, v167
	global_store_dwordx4 v2, v[136:139], s[6:7]
	global_store_dwordx4 v2, v[140:143], s[6:7] offset:1024
	global_store_dwordx4 v2, v[144:147], s[6:7] offset:2048
	global_store_dwordx4 v2, v[148:151], s[6:7] offset:3072
	global_store_dwordx4 v2, v[152:155], s[24:25]
	global_store_dwordx4 v2, v[156:159], s[24:25] offset:1024
	global_store_dwordx4 v2, v[160:163], s[24:25] offset:2048
	global_store_dwordx4 v2, v[164:167], s[24:25] offset:3072
	s_add_u32 s6, s6, s21
	s_addc_u32 s7, s7, 0
	s_add_u32 s24, s24, s21
	s_addc_u32 s25, s25, 0
	s_mov_b32 s60, s22
	s_cmp_gt_i32 s60, 0x7fff
	s_cbranch_scc1 .LBB0_2215
.Lmy_fin_B:
	s_add_i32 s22, s60, s54
	s_cmp_gt_i32 s22, 0x7fff
	s_cbranch_scc1 .Lmy_fin_last_B
	s_add_u32 s2, s2, s20
	s_addc_u32 s3, s3, 0
	s_add_u32 s4, s4, s20
	s_addc_u32 s5, s5, 0
	global_load_dwordx2 v[72:73], v1, s[2:3]
	global_load_dwordx2 v[74:75], v1, s[2:3] offset:512
	global_load_dwordx2 v[76:77], v1, s[2:3] offset:1024
	global_load_dwordx2 v[78:79], v1, s[2:3] offset:1536
	global_load_dwordx2 v[80:81], v1, s[2:3] offset:2048
	global_load_dwordx2 v[82:83], v1, s[2:3] offset:2560
	global_load_dwordx2 v[84:85], v1, s[2:3] offset:3072
	global_load_dwordx2 v[86:87], v1, s[2:3] offset:3584
	global_load_dwordx2 v[88:89], v1, s[4:5]
	global_load_dwordx2 v[90:91], v1, s[4:5] offset:512
	global_load_dwordx2 v[92:93], v1, s[4:5] offset:1024
	global_load_dwordx2 v[94:95], v1, s[4:5] offset:1536
	global_load_dwordx2 v[96:97], v1, s[4:5] offset:2048
	global_load_dwordx2 v[98:99], v1, s[4:5] offset:2560
	global_load_dwordx2 v[100:101], v1, s[4:5] offset:3072
	global_load_dwordx2 v[102:103], v1, s[4:5] offset:3584
	s_cmp_eq_u32 s17, 0
	s_cbranch_scc1 .Lmy_fin_w24_B
	s_waitcnt vmcnt(16)
	s_mov_b32 s17, 0

; __device__ __forceinline__ float bf_lo(unsigned w) { return __uint_as_float(w << 16); }
; __device__ __forceinline__ float bf_hi(unsigned w) { return __uint_as_float(w & 0xffff0000u); }
; __device__ __forceinline__ void peer_final(Frame& F, const Params& p) {
;     ...
;         for (int j = 0; j < 8; ++j) {
;             const int el = 4 * lane + 256 * j; const f32x4 g4 = *(const f32x4*)(m5 + el);
;             const float mf[4] = {bf_lo(r.m[j].x), bf_hi(r.m[j].x), bf_lo(r.m[j].y), bf_hi(r.m[j].y)}, pf[4] = {bf_lo(r.q[j].x), bf_hi(r.q[j].x), bf_lo(r.q[j].y), bf_hi(r.q[j].y)};
; #pragma unroll
;             for (int i = 0; i < 4; ++i) { const float t = mf[i] + g4[i] * pf[i]; v[j][i] = t; ss += t * t; }
.Lmy_fin_nob_B:
	v_lshlrev_b32_e32 v168, 16, v104
	v_and_b32_e32 v169, s26, v104
	v_lshlrev_b32_e32 v170, 16, v105
	v_and_b32_e32 v171, s26, v105
	v_lshlrev_b32_e32 v172, 16, v120
	v_and_b32_e32 v173, s26, v120
	v_lshlrev_b32_e32 v174, 16, v121
	v_and_b32_e32 v175, s26, v121
	v_fma_f32 v136, v40, v172, v168
	v_fma_f32 v137, v41, v173, v169
	v_fma_f32 v138, v42, v174, v170
	v_fma_f32 v139, v43, v175, v171
	v_mul_f32_e32 v200, v136, v136
	v_mul_f32_e32 v201, v137, v137
	v_fmac_f32_e32 v200, v138, v138
	v_fmac_f32_e32 v201, v139, v139
	v_lshlrev_b32_e32 v168, 16, v106
	v_and_b32_e32 v169, s26, v106
	v_lshlrev_b32_e32 v170, 16, v107
	v_and_b32_e32 v171, s26, v107
	v_lshlrev_b32_e32 v172, 16, v122
	v_and_b32_e32 v173, s26, v122
	v_lshlrev_b32_e32 v174, 16, v123
	v_and_b32_e32 v175, s26, v123
	v_fma_f32 v140, v44, v172, v168
	v_fma_f32 v141, v45, v173, v169
	v_fma_f32 v142, v46, v174, v170
	v_fma_f32 v143, v47, v175, v171
	v_fmac_f32_e32 v200, v140, v140
	v_fmac_f32_e32 v201, v141, v141
	v_fmac_f32_e32 v200, v142, v142
	v_fmac_f32_e32 v201, v143, v143
	v_lshlrev_b32_e32 v168, 16, v108
	v_and_b32_e32 v169, s26, v108
	v_lshlrev_b32_e32 v170, 16, v109
	v_and_b32_e32 v171, s26, v109
	v_lshlrev_b32_e32 v172, 16, v124
	v_and_b32_e32 v173, s26, v124
	v_lshlrev_b32_e32 v174, 16, v125
	v_and_b32_e32 v175, s26, v125
	v_fma_f32 v144, v48, v172, v168
	v_fma_f32 v145, v49, v173, v169
	v_fma_f32 v146, v50, v174, v170
	v_fma_f32 v147, v51, v175, v171
	v_fmac_f32_e32 v200, v144, v144
	v_fmac_f32_e32 v201, v145, v145
	v_fmac_f32_e32 v200, v146, v146
	v_fmac_f32_e32 v201, v147, v147
	v_lshlrev_b32_e32 v168, 16, v110
	v_and_b32_e32 v169, s26, v110
	v_lshlrev_b32_e32 v170, 16, v111
	v_and_b32_e32 v171, s26, v111
	v_lshlrev_b32_e32 v172, 16, v126
	v_and_b32_e32 v173, s26, v126
	v_lshlrev_b32_e32 v174, 16, v127
	v_and_b32_e32 v175, s26, v127
	v_fma_f32 v148, v52, v172, v168
	v_fma_f32 v149, v53, v173, v169
	v_fma_f32 v150, v54, v174, v170
	v_fma_f32 v151, v55, v175, v171
	v_fmac_f32_e32 v200, v148, v148
	v_fmac_f32_e32 v201, v149, v149
	v_fmac_f32_e32 v200, v150, v150
	v_fmac_f32_e32 v201, v151, v151
	v_lshlrev_b32_e32 v168, 16, v112
	v_and_b32_e32 v169, s26, v112
	v_lshlrev_b32_e32 v170, 16, v113
	v_and_b32_e32 v171, s26, v113
	v_lshlrev_b32_e32 v172, 16, v128
	v_and_b32_e32 v173, s26, v128
	v_lshlrev_b32_e32 v174, 16, v129
	v_and_b32_e32 v175, s26, v129
	v_fma_f32 v152, v56, v172, v168
	v_fma_f32 v153, v57, v173, v169
	v_fma_f32 v154, v58, v174, v170
	v_fma_f32 v155, v59, v175, v171
	v_fmac_f32_e32 v200, v152, v152
	v_fmac_f32_e32 v201, v153, v153
	v_fmac_f32_e32 v200, v154, v154
	v_fmac_f32_e32 v201, v155, v155
	v_lshlrev_b32_e32 v168, 16, v114
	v_and_b32_e32 v169, s26, v114
	v_lshlrev_b32_e32 v170, 16, v115
	v_and_b32_e32 v171, s26, v115
	v_lshlrev_b32_e32 v172, 16, v130
	v_and_b32_e32 v173, s26, v130
	v_lshlrev_b32_e32 v174, 16, v131
	v_and_b32_e32 v175, s26, v131
	v_fma_f32 v156, v60, v172, v168
	v_fma_f32 v157, v61, v173, v169
	v_fma_f32 v158, v62, v174, v170
	v_fma_f32 v159, v63, v175, v171
	v_fmac_f32_e32 v200, v156, v156
	v_fmac_f32_e32 v201, v157, v157
	v_fmac_f32_e32 v200, v158, v158
	v_fmac_f32_e32 v201, v159, v159
	v_lshlrev_b32_e32 v168, 16, v116
	v_and_b32_e32 v169, s26, v116
	v_lshlrev_b32_e32 v170, 16, v117
	v_and_b32_e32 v171, s26, v117
	v_lshlrev_b32_e32 v172, 16, v132
	v_and_b32_e32 v173, s26, v132
	v_lshlrev_b32_e32 v174, 16, v133
	v_and_b32_e32 v175, s26, v133
	v_fma_f32 v160, v64, v172, v168
	v_fma_f32 v161, v65, v173, v169
	v_fma_f32 v162, v66, v174, v170
	v_fma_f32 v163, v67, v175, v171
	v_fmac_f32_e32 v200, v160, v160
	v_fmac_f32_e32 v201, v161, v161
	v_fmac_f32_e32 v200, v162, v162
	v_fmac_f32_e32 v201, v163, v163
	v_lshlrev_b32_e32 v168, 16, v118
	v_and_b32_e32 v169, s26, v118
	v_lshlrev_b32_e32 v170, 16, v119
; __device__ __forceinline__ void peer_final(Frame& F, const Params& p) {
;     ...
;             for (int i = 0; i < 4; ++i) { const float t = mf[i] + g4[i] * pf[i]; v[j][i] = t; ss += t * t; }
;         }
;         const float rstd = rsqrtf(wave_sum(ss, lane) * (1.f / D) + 1e-6f);
; #pragma unroll
;         for (int j = 0; j < 8; ++j) {
;             const int el = 4 * lane + 256 * j; const f32x4 gf = *(const f32x4*)(p.in[32] + el);
;             *(f32x4*)(hrow + el) = (f32x4){v[j][0] * rstd * gf[0], v[j][1] * rstd * gf[1], v[j][2] * rstd * gf[2], v[j][3] * rstd * gf[3]};
;         }
;     }
	v_and_b32_e32 v171, s26, v119
	v_lshlrev_b32_e32 v172, 16, v134
	v_and_b32_e32 v173, s26, v134
	v_lshlrev_b32_e32 v174, 16, v135
	v_and_b32_e32 v175, s26, v135
	v_fma_f32 v164, v68, v172, v168
	v_fma_f32 v165, v69, v173, v169
	v_fma_f32 v166, v70, v174, v170
	v_fma_f32 v167, v71, v175, v171
	v_fmac_f32_e32 v200, v164, v164
	v_fmac_f32_e32 v201, v165, v165
	v_fmac_f32_e32 v200, v166, v166
	v_fmac_f32_e32 v201, v167, v167
	v_add_f32_e32 v200, v200, v201
	s_nop 1
	v_add_f32_dpp v200, v200, v200 quad_perm:[1,0,3,2] row_mask:0xf bank_mask:0xf
	s_nop 1
	v_add_f32_dpp v200, v200, v200 quad_perm:[2,3,0,1] row_mask:0xf bank_mask:0xf
	s_nop 1
	v_add_f32_dpp v200, v200, v200 row_half_mirror row_mask:0xf bank_mask:0xf
	s_nop 1
	v_add_f32_dpp v200, v200, v200 row_mirror row_mask:0xf bank_mask:0xf
	s_nop 1
	v_readlane_b32 s27, v200, 0
	v_readlane_b32 s28, v200, 16
	v_readlane_b32 s29, v200, 32
	v_readlane_b32 s30, v200, 48
	s_nop 1
	v_mov_b32_e32 v201, s27
	v_add_f32_e32 v201, s28, v201
	v_add_f32_e32 v201, s29, v201
	v_add_f32_e32 v201, s30, v201
	v_fmamk_f32 v201, v201, 0x3a000000, v202
	v_rsq_f32_e32 v201, v201
	s_nop 0
	v_mul_f32_e32 v136, v136, v201
	v_mul_f32_e32 v137, v137, v201
	v_mul_f32_e32 v138, v138, v201
	v_mul_f32_e32 v139, v139, v201
	v_mul_f32_e32 v140, v140, v201
	v_mul_f32_e32 v141, v141, v201
	v_mul_f32_e32 v142, v142, v201
	v_mul_f32_e32 v143, v143, v201
	v_mul_f32_e32 v144, v144, v201
	v_mul_f32_e32 v145, v145, v201
	v_mul_f32_e32 v146, v146, v201
	v_mul_f32_e32 v147, v147, v201
	v_mul_f32_e32 v148, v148, v201
	v_mul_f32_e32 v149, v149, v201
	v_mul_f32_e32 v150, v150, v201
	v_mul_f32_e32 v151, v151, v201
	v_mul_f32_e32 v152, v152, v201
	v_mul_f32_e32 v153, v153, v201
	v_mul_f32_e32 v154, v154, v201
	v_mul_f32_e32 v155, v155, v201
	v_mul_f32_e32 v156, v156, v201
	v_mul_f32_e32 v157, v157, v201
	v_mul_f32_e32 v158, v158, v201
	v_mul_f32_e32 v159, v159, v201
	v_mul_f32_e32 v160, v160, v201
	v_mul_f32_e32 v161, v161, v201
	v_mul_f32_e32 v162, v162, v201
	v_mul_f32_e32 v163, v163, v201
	v_mul_f32_e32 v164, v164, v201
	v_mul_f32_e32 v165, v165, v201
	v_mul_f32_e32 v166, v166, v201
	v_mul_f32_e32 v167, v167, v201
	v_mul_f32_e32 v136, v8, v136
	v_mul_f32_e32 v137, v9, v137
	v_mul_f32_e32 v138, v10, v138
	v_mul_f32_e32 v139, v11, v139
	v_mul_f32_e32 v140, v12, v140
	v_mul_f32_e32 v141, v13, v141
	v_mul_f32_e32 v142, v14, v142
	v_mul_f32_e32 v143, v15, v143
	v_mul_f32_e32 v144, v16, v144
	v_mul_f32_e32 v145, v17, v145
	v_mul_f32_e32 v146, v18, v146
	v_mul_f32_e32 v147, v19, v147
	v_mul_f32_e32 v148, v20, v148
	v_mul_f32_e32 v149, v21, v149
	v_mul_f32_e32 v150, v22, v150
	v_mul_f32_e32 v151, v23, v151
	v_mul_f32_e32 v152, v24, v152
	v_mul_f32_e32 v153, v25, v153
	v_mul_f32_e32 v154, v26, v154
	v_mul_f32_e32 v155, v27, v155
	v_mul_f32_e32 v156, v28, v156
	v_mul_f32_e32 v157, v29, v157
	v_mul_f32_e32 v158, v30, v158
	v_mul_f32_e32 v159, v31, v159
	v_mul_f32_e32 v160, v32, v160
	v_mul_f32_e32 v161, v33, v161
	v_mul_f32_e32 v162, v34, v162
	v_mul_f32_e32 v163, v35, v163
	v_mul_f32_e32 v164, v36, v164
	v_mul_f32_e32 v165, v37, v165
	v_mul_f32_e32 v166, v38, v166
	v_mul_f32_e32 v167, v39, v167
	global_store_dwordx4 v2, v[136:139], s[6:7]
	global_store_dwordx4 v2, v[140:143], s[6:7] offset:1024
	global_store_dwordx4 v2, v[144:147], s[6:7] offset:2048
	global_store_dwordx4 v2, v[148:151], s[6:7] offset:3072
	global_store_dwordx4 v2, v[152:155], s[24:25]
	global_store_dwordx4 v2, v[156:159], s[24:25] offset:1024
	global_store_dwordx4 v2, v[160:163], s[24:25] offset:2048
	global_store_dwordx4 v2, v[164:167], s[24:25] offset:3072
	s_add_u32 s6, s6, s21
	s_addc_u32 s7, s7, 0
	s_add_u32 s24, s24, s21
	s_addc_u32 s25, s25, 0
	s_mov_b32 s60, s22
	s_cmp_gt_i32 s60, 0x7fff
	s_cbranch_scc1 .LBB0_2215
	s_branch .Lmy_fin_loop
